# weight transpose LDS tile re-laid out: row pitch 260 floats with 16B-chunk XOR swizzle by (row>>3); staging writes are 8 conflict-free ds_write_b128 (were 16 ds_write2_b32 with 8-way bank conflicts),
# baseline (speedup 1.0000x reference)
.LBB0_566:
	s_andn2_b64 vcc, exec, s[0:1]
	s_cbranch_vccnz .LBB0_9
	v_add_u32_e32 v47, 0x400, v34
	v_ashrrev_i32_e32 v45, 3, v35
	v_and_b32_e32 v60, 56, v33
	v_lshlrev_b32_e32 v61, 1, v60
	s_movk_i32 s0, 0x410
	v_ashrrev_i32_e32 v38, 6, v35
	v_ashrrev_i32_e32 v39, 6, v47
	v_add_u32_e32 v49, 0x600, v34
	v_lshlrev_b32_e32 v35, 2, v45
	v_ashrrev_i32_e32 v47, 3, v47
	v_ashrrev_i32_e32 v36, 3, v34
	v_ashrrev_i32_e32 v40, 6, v49
	v_add_u32_e32 v41, 0x800, v34
	v_add_u32_e32 v42, 0xa00, v34
	v_add_u32_e32 v43, 0xc00, v34
	v_add_u32_e32 v34, 0xe00, v34
	v_xor_b32_e32 v35, v35, v61
	v_mad_u32_u24 v46, v60, s0, v35
	v_lshlrev_b32_e32 v35, 2, v47
	v_ashrrev_i32_e32 v49, 3, v49
	v_lshlrev_b32_e32 v33, 2, v36
	v_ashrrev_i32_e32 v41, 6, v41
	v_ashrrev_i32_e32 v42, 6, v42
	v_ashrrev_i32_e32 v43, 6, v43
	v_ashrrev_i32_e32 v44, 6, v34
	v_xor_b32_e32 v35, v35, v61
	v_mad_u32_u24 v48, v60, s0, v35
	v_lshlrev_b32_e32 v35, 2, v49
	v_xor_b32_e32 v33, v33, v61
	v_mad_u32_u24 v37, v60, s0, v33
	v_mul_lo_u32 v33, v52, s0
	v_mul_lo_u32 v53, v38, s0
	v_mul_lo_u32 v54, v39, s0
	v_mul_lo_u32 v55, v40, s0
	v_mul_lo_u32 v56, v41, s0
	v_mul_lo_u32 v57, v42, s0
	v_mul_lo_u32 v58, v43, s0
	v_mul_lo_u32 v34, v44, s0
	v_xor_b32_e32 v35, v35, v61
	v_mad_u32_u24 v50, v60, s0, v35
	s_sub_i32 s0, s56, s48
	s_sub_i32 s0, s0, s51
	s_sub_i32 s6, s0, s53
	s_add_i32 s0, s55, s56
	s_sub_i32 s0, s0, s48
	v_lshlrev_b32_e32 v59, 2, v32
	s_sub_i32 s9, 0, s48
	s_sub_i32 s0, s0, s51
	s_sub_i32 s12, s55, s48
	s_mov_b32 s7, 0
	s_sub_i32 s10, s9, s51
	s_sub_i32 s11, s0, s53
	s_sub_i32 s13, s12, s51
	v_add_u32_e32 v51, v59, v33
	v_xor_b32_e32 v61, 16, v59
	v_add_u32_e32 v53, v61, v53
	v_xor_b32_e32 v61, 32, v59
	v_add_u32_e32 v54, v61, v54
	v_xor_b32_e32 v61, 48, v59
	v_add_u32_e32 v55, v61, v55
	v_xor_b32_e32 v61, 64, v59
	v_add_u32_e32 v56, v61, v56
	v_xor_b32_e32 v61, 80, v59
	v_add_u32_e32 v57, v61, v57
	v_xor_b32_e32 v61, 96, v59
	v_add_u32_e32 v58, v61, v58
	v_xor_b32_e32 v61, 112, v59
	v_add_u32_e32 v59, v61, v34
	v_lshlrev_b32_e32 v144, 2, v32
	v_lshlrev_b32_e32 v32, 1, v60
	s_mov_b32 s14, s55
	s_mov_b32 s15, s54
	s_branch .LBB0_570

.LBB0_569:
	v_cvt_f32_u32_e32 v33, s35
	s_sub_i32 s4, 0, s35
	s_abs_i32 s1, s34
	s_ashr_i32 s0, s34, 31
	v_rcp_iflag_f32_e32 v33, v33
	s_nop 0
	v_mul_f32_e32 v33, 0x4f7ffffe, v33
	v_cvt_u32_f32_e32 v33, v33
	s_nop 0
	v_readfirstlane_b32 s5, v33
	s_mul_i32 s4, s4, s5
	s_mul_hi_u32 s4, s5, s4
	s_add_i32 s5, s5, s4
	s_mul_hi_u32 s4, s1, s5
	s_mul_i32 s5, s4, s35
	s_sub_i32 s1, s1, s5
	s_add_i32 s5, s4, 1
	s_sub_i32 s36, s1, s35
	s_cmp_ge_u32 s1, s35
	s_cselect_b32 s4, s5, s4
	s_cselect_b32 s1, s36, s1
	s_add_i32 s5, s4, 1
	s_cmp_ge_u32 s1, s35
	s_cselect_b32 s1, s5, s4
	s_xor_b32 s1, s1, s0
	s_sub_i32 s1, s1, s0
	s_lshl_b32 s4, s1, 6
	s_ashr_i32 s5, s4, 31
	s_lshl_b64 s[4:5], s[4:5], 1
	v_lshl_add_u64 v[34:35], v[34:35], 0, s[4:5]
	v_mov_b32_e32 v33, v145
	v_lshl_add_u64 v[34:35], v[34:35], 0, v[32:33]
	ds_read_b32 v33, v37
	ds_read_b32 v60, v37 offset:1040
	s_waitcnt lgkmcnt(0)
	v_cvt_pk_bf16_f32 v60, v33, v60
	ds_read_b32 v33, v37 offset:2080
	ds_read_b32 v61, v37 offset:3120
	s_waitcnt lgkmcnt(0)
	v_cvt_pk_bf16_f32 v61, v33, v61
	ds_read_b32 v33, v37 offset:4160
	ds_read_b32 v62, v37 offset:5200
	s_waitcnt lgkmcnt(0)
	v_cvt_pk_bf16_f32 v62, v33, v62
	ds_read_b32 v33, v37 offset:6240
	ds_read_b32 v63, v37 offset:7280
	s_mul_i32 s0, s1, s35
	s_sub_i32 s0, s34, s0
	s_lshl_b32 s0, s0, 8
	s_waitcnt lgkmcnt(0)
	v_cvt_pk_bf16_f32 v63, v33, v63
	v_add_u32_e32 v33, s0, v36
	v_mad_i64_i32 v[64:65], s[4:5], v33, s70, v[34:35]
	global_store_dwordx4 v[64:65], v[60:63], off
	ds_read_b32 v33, v46
	ds_read_b32 v60, v46 offset:1040
	s_waitcnt lgkmcnt(0)
	v_cvt_pk_bf16_f32 v60, v33, v60
	ds_read_b32 v33, v46 offset:2080
	ds_read_b32 v61, v46 offset:3120
	s_waitcnt lgkmcnt(0)
	v_cvt_pk_bf16_f32 v61, v33, v61
	ds_read_b32 v33, v46 offset:4160
	ds_read_b32 v62, v46 offset:5200
	s_waitcnt lgkmcnt(0)
	v_cvt_pk_bf16_f32 v62, v33, v62
	ds_read_b32 v33, v46 offset:6240
	ds_read_b32 v63, v46 offset:7280
	s_waitcnt lgkmcnt(0)
	v_cvt_pk_bf16_f32 v63, v33, v63
	v_add_u32_e32 v33, s0, v45
	v_mad_i64_i32 v[64:65], s[4:5], v33, s70, v[34:35]
	global_store_dwordx4 v[64:65], v[60:63], off
	ds_read_b32 v33, v48
	ds_read_b32 v60, v48 offset:1040
	s_waitcnt lgkmcnt(0)
	v_cvt_pk_bf16_f32 v60, v33, v60
	ds_read_b32 v33, v48 offset:2080
	ds_read_b32 v61, v48 offset:3120
	s_waitcnt lgkmcnt(0)
	v_cvt_pk_bf16_f32 v61, v33, v61
	ds_read_b32 v33, v48 offset:4160
	ds_read_b32 v62, v48 offset:5200
	s_waitcnt lgkmcnt(0)
	v_cvt_pk_bf16_f32 v62, v33, v62
	ds_read_b32 v33, v48 offset:6240
	ds_read_b32 v63, v48 offset:7280
	s_waitcnt lgkmcnt(0)
	v_cvt_pk_bf16_f32 v63, v33, v63
	v_add_u32_e32 v33, s0, v47
	v_mad_i64_i32 v[64:65], s[4:5], v33, s70, v[34:35]
	global_store_dwordx4 v[64:65], v[60:63], off
	ds_read_b32 v33, v50
	ds_read_b32 v60, v50 offset:1040
	s_waitcnt lgkmcnt(0)
	v_cvt_pk_bf16_f32 v60, v33, v60
	ds_read_b32 v33, v50 offset:2080
	ds_read_b32 v61, v50 offset:3120
	s_waitcnt lgkmcnt(0)
	v_cvt_pk_bf16_f32 v61, v33, v61
	ds_read_b32 v33, v50 offset:4160
	ds_read_b32 v62, v50 offset:5200
	s_waitcnt lgkmcnt(0)
	v_cvt_pk_bf16_f32 v62, v33, v62
	ds_read_b32 v33, v50 offset:6240
	ds_read_b32 v63, v50 offset:7280
	s_waitcnt lgkmcnt(0)
	v_cvt_pk_bf16_f32 v63, v33, v63
	v_add_u32_e32 v33, s0, v49
	v_mad_i64_i32 v[34:35], s[0:1], v33, s70, v[34:35]
	s_add_i32 s7, s7, s55
	s_add_i32 s6, s6, s55
	s_add_i32 s10, s10, s55
	s_add_i32 s9, s9, s55
	s_add_i32 s11, s11, s55
	s_add_i32 s13, s13, s55
	s_add_i32 s12, s12, s55
	s_add_i32 s14, s14, s55
	s_add_i32 s0, s54, s7
	s_cmp_ge_i32 s0, s8
	global_store_dwordx4 v[34:35], v[60:63], off
	s_barrier
	s_cbranch_scc1 .LBB0_9

.Ltr_wr:
	ds_write_b128 v51, v[192:195]
	ds_write_b128 v53, v[188:191]
	ds_write_b128 v54, v[200:203]
	ds_write_b128 v55, v[196:199]
	ds_write_b128 v56, v[208:211]
	ds_write_b128 v57, v[204:207]
	ds_write_b128 v58, v[216:219]
	ds_write_b128 v59, v[212:215]
	s_waitcnt lgkmcnt(0)
	s_barrier
	s_branch .LBB0_569
